# DSA unit prologue: Q loads issued before the mask wait; the wait before the first MFMA no longer covers the just-issued third K tile
# speedup vs baseline: 1.0190x; 1.0006x over previous
; #define WAIT_BAR(N) asm volatile("s_waitcnt vmcnt(" #N ") lgkmcnt(0)\n\ts_barrier":::"memory")
;   #define DMA_K(t,slot) glds16(ksrc+(long)(t)*KVBLK*KP,(unsigned)__builtin_amdgcn_readfirstlane(kdst+(slot)))
;   #define DMA_V(t,slot) glds16(vsrc+(long)(t)*KVBLK*VP,(unsigned)__builtin_amdgcn_readfirstlane(vdst+(slot)))
;   #define XMASK(P0,P1,t) do{ if constexpr(MASKED){ bmask(P0,P1,mimg[(2*(t))*32],mimg[(2*(t)+1)*32],hi); } else { CMASK(P0,P1,t); } }while(0)
;     ...
;   DMA_K(0,0);DMA_V(0,0);DMA_K(1,SLOTB);
;   if constexpr(MASKED){
;     __attribute__((address_space(3))) u32x4* mdst=(__attribute__((address_space(3))) u32x4*)(shm3+LDS_OST+wid*MWAVE)+lane;
;     for(int i=0;i<=qb;++i){ const u32x4 v=((const u32x4*)mwave)[i*64+lane]; mdst[i*64]=v; }
;   }
;   bf16x8 qr[4];
;   #pragma unroll
;   for(int d0=0;d0<4;++d0)qr[d0]=*reinterpret_cast<const bf16x8*>(&Qw[(long)r32*QP+d0*16+hi*8]);
;   float mhat=0.f,l_reg=0.f;f32x16 o[2];o[0]=f32x16{};o[1]=f32x16{};f32x16 negm=f32x16{};asm volatile("":"+v"(negm));
;   const int qrel=wid*QBLK+r32;
;     ...
;   bool resc=false;
;     ...
;   f32x16 pA0,pA1,pB0,pB1;
;   int sl_prev=0,sl_cur=0,sl_next=SLOTB;
;     ...
;   DMA_K(2,2*SLOTB);
;   WAIT_BAR(3);
;   qkt(pA0,pA1,Kbase,qr,negm,r32,hi);asm volatile("s_nop 15\n\ts_nop 7":"+v"(pA0),"+v"(pA1));XMASK(pA0,pA1,0);
.Ldm_wait:
	s_cmp_lg_u32 s79, 0
	s_cselect_b64 s[2:3], -1, 0
	s_lshl_b32 s30, s1, 5
	s_ashr_i32 s31, s30, 31
	s_lshl_b64 s[4:5], s[30:31], 10
	s_and_b32 s22, s0, 0x3fffffc0
	s_add_i32 s29, s78, 0x100
	v_readlane_b32 s0, v254, 17
	s_add_u32 s0, s0, s34
	s_addc_u32 s1, s55, s35
	s_lshl_b32 s8, s28, 7
	s_add_u32 s0, s0, s8
	v_and_b32_e32 v215, 31, v42
	s_addc_u32 s1, s1, 0
	v_lshrrev_b32_e32 v43, 5, v46
	s_add_u32 s0, s0, s4
	v_lshlrev_b32_e32 v0, 10, v215
	s_addc_u32 s1, s1, s5
	v_lshl_or_b32 v9, v43, 4, v0
	global_load_dwordx4 v[166:169], v9, s[0:1]
	global_load_dwordx4 v[162:165], v9, s[0:1] offset:32
	global_load_dwordx4 v[36:39], v9, s[0:1] offset:64
	global_load_dwordx4 v[32:35], v9, s[0:1] offset:96
	s_waitcnt vmcnt(4)
	ds_write_b128 v4, v[100:103] offset:51200
	s_cmp_lt_u32 s79, 1
	s_cbranch_scc1 .LBB0_1521
	ds_write_b128 v4, v[104:107] offset:52224
	s_cmp_lt_u32 s79, 2
	s_cbranch_scc1 .LBB0_1521
	ds_write_b128 v4, v[108:111] offset:53248
	s_cmp_lt_u32 s79, 3
	s_cbranch_scc1 .LBB0_1521
	ds_write_b128 v4, v[112:115] offset:54272
	s_cmp_lt_u32 s79, 4
	s_cbranch_scc1 .LBB0_1521
	ds_write_b128 v4, v[116:119] offset:55296
	s_cmp_lt_u32 s79, 5
	s_cbranch_scc1 .LBB0_1521
	ds_write_b128 v4, v[120:123] offset:56320
	s_cmp_lt_u32 s79, 6
	s_cbranch_scc1 .LBB0_1521
	ds_write_b128 v4, v[124:127] offset:57344
	s_cmp_lt_u32 s79, 7
	s_cbranch_scc1 .LBB0_1521
	ds_write_b128 v4, v[128:131] offset:58368
.LBB0_1521:
	v_mov_b32_e32 v14, v1
	v_mov_b32_e32 v15, v1
	v_mov_b32_e32 v0, v1
	v_mov_b32_e32 v2, v1
	v_mov_b32_e32 v3, v1
	v_mov_b32_e32 v4, v1
	v_mov_b32_e32 v5, v1
	v_mov_b32_e32 v6, v1
	v_mov_b32_e32 v7, v1
	v_mov_b32_e32 v8, v1
	v_mov_b32_e32 v9, v1
	v_mov_b32_e32 v10, v1
	v_mov_b32_e32 v11, v1
	v_mov_b32_e32 v12, v1
	v_mov_b32_e32 v13, v1
	v_mov_b64_e32 v[62:63], v[14:15]
	v_mov_b64_e32 v[60:61], v[12:13]
	v_mov_b64_e32 v[58:59], v[10:11]
	v_mov_b64_e32 v[56:57], v[8:9]
	v_mov_b64_e32 v[54:55], v[6:7]
	v_mov_b64_e32 v[52:53], v[4:5]
	v_mov_b64_e32 v[50:51], v[2:3]
	v_mov_b64_e32 v[48:49], v[0:1]
	v_lshl_add_u64 v[64:65], v[44:45], 0, s[20:21]
	v_lshlrev_b32_e32 v66, 10, v43
	v_lshlrev_b32_e32 v67, 4, v215
	s_add_i32 s0, s48, 0x4000
	s_mov_b32 s1, m0
	s_mov_b32 m0, s0
	s_nop 0
	global_load_lds_dwordx4 v[64:65], off
	s_mov_b32 m0, s1
	v_add3_u32 v227, 0, v66, v67
	s_waitcnt vmcnt(3) lgkmcnt(0)
	s_barrier
	ds_read_b128 v[2:5], v227
	ds_read_b128 v[6:9], v227 offset:512
	v_lshl_add_u32 v223, v215, 2, s46
	v_lshlrev_b32_e32 v0, 1, v42
	v_lshlrev_b32_e32 v10, 4, v42
	v_and_b32_e32 v221, 32, v0
	v_lshlrev_b32_e32 v0, 8, v43
	v_lshlrev_b32_e32 v224, 2, v43
	v_and_or_b32 v220, v10, s73, v0
	s_lshl_b32 s0, s22, 2
	s_add_i32 s47, s0, 0
	v_lshlrev_b32_e32 v210, 2, v215
	s_mov_b32 s8, 1
	s_mov_b32 s34, 0
	s_movk_i32 s44, 0x4000
	s_lshr_b32 s50, s29, 6
	s_movk_i32 s51, 0x2000
	s_and_b64 vcc, exec, s[2:3]
	v_cmp_gt_u32_e64 s[2:3], 32, v46
	v_add_u32_e32 v228, s47, v210
	v_lshl_add_u32 v222, v224, 2, s47
	s_waitcnt vmcnt(1) lgkmcnt(0)
	v_mfma_f32_32x32x16_bf16 v[64:79], v[2:5], v[166:169], v[48:63]
	v_mfma_f32_32x32x16_bf16 v[48:63], v[6:9], v[166:169], v[48:63]
	ds_read_b128 v[2:5], v227 offset:2048
	ds_read_b128 v[6:9], v227 offset:2560
	s_waitcnt lgkmcnt(1)
	v_mfma_f32_32x32x16_bf16 v[64:79], v[2:5], v[162:165], v[64:79]
	s_waitcnt lgkmcnt(0)
	v_mfma_f32_32x32x16_bf16 v[48:63], v[6:9], v[162:165], v[48:63]
	ds_read_b128 v[2:5], v227 offset:4096
	ds_read_b128 v[6:9], v227 offset:4608
	s_waitcnt lgkmcnt(1)
	v_mfma_f32_32x32x16_bf16 v[64:79], v[2:5], v[36:39], v[64:79]
	ds_read_b128 v[2:5], v227 offset:6144
	s_waitcnt lgkmcnt(1)
	v_mfma_f32_32x32x16_bf16 v[48:63], v[6:9], v[36:39], v[48:63]
	ds_read_b128 v[6:9], v227 offset:6656
	s_waitcnt lgkmcnt(1)
	v_mfma_f32_32x32x16_bf16 v[64:79], v[2:5], v[32:35], v[64:79]
	v_add_u32_e32 v2, 0xc800, v223
	v_add_u32_e32 v4, 0, v221
	v_add3_u32 v226, v4, v219, v220
	s_waitcnt lgkmcnt(0)
	v_mfma_f32_32x32x16_bf16 v[48:63], v[6:9], v[32:35], v[48:63]
	s_nop 15
	s_nop 7
	ds_read2_b32 v[2:3], v2 offset1:32
	s_waitcnt lgkmcnt(0)
; #define WAIT_BAR(N) asm volatile("s_waitcnt vmcnt(" #N ") lgkmcnt(0)\n\ts_barrier":::"memory")
;   #define DMA_K(t,slot) glds16(ksrc+(long)(t)*KVBLK*KP,(unsigned)__builtin_amdgcn_readfirstlane(kdst+(slot)))
;   #define DMA_V(t,slot) glds16(vsrc+(long)(t)*KVBLK*VP,(unsigned)__builtin_amdgcn_readfirstlane(vdst+(slot)))
;   #define XMASK(P0,P1,t) do{ if constexpr(MASKED){ bmask(P0,P1,mimg[(2*(t))*32],mimg[(2*(t)+1)*32],hi); } else { CMASK(P0,P1,t); } }while(0)
;   #define ROT() do{sl_prev=sl_cur;sl_cur=sl_next;sl_next=(sl_next==(NSLOT-1)*SLOTB)?0:sl_next+SLOTB;}while(0)
; __device__ __forceinline__ void bmask(f32x16&p0,f32x16&p1,unsigned w0,unsigned w1,int hi){
;   const unsigned m0=w0>>(4*hi), m1=w1>>(4*hi); const unsigned NEGB=0xff800000u;
;   #pragma unroll
;   for(int r=0;r<16;++r){
;     int t0,t1; asm("v_bfe_i32 %0, %1, %2, 1":"=v"(t0):"v"(m0),"n"(cr0(r))); asm("v_bfe_i32 %0, %1, %2, 1":"=v"(t1):"v"(m1),"n"(cr0(r)));
;     asm("v_bfi_b32 %0, %1, %0, %2":"+v"(p0[r]):"v"(t0),"v"(NEGB)); asm("v_bfi_b32 %0, %1, %0, %2":"+v"(p1[r]):"v"(t1),"v"(NEGB)); }
; }
;     ...
;   f32x16 pA0,pA1,pB0,pB1;
;   int sl_prev=0,sl_cur=0,sl_next=SLOTB;
;     ...
;   DMA_K(2,2*SLOTB);
;   WAIT_BAR(3);
;   qkt(pA0,pA1,Kbase,qr,negm,r32,hi);asm volatile("s_nop 15\n\ts_nop 7":"+v"(pA0),"+v"(pA1));XMASK(pA0,pA1,0);
;   START(pA0,pA1);
;   _Pragma("unroll") for(int r=0;r<16;++r)pA1[r]=__builtin_amdgcn_exp2f(pA1[r]);
;   WAIT_BAR(0);
;   DMA_K(3,0);DMA_V(1,SLOTB);
;   ROT();
;   kload8(kf,kp0+sl_cur);
;   WAIT_BAR(2);
	v_lshrrev_b32_e32 v2, v224, v2
	v_bfe_i32 v4, v2, 0, 1
	v_lshrrev_b32_e32 v3, v224, v3
	v_bfi_b32 v64, v4, v64, v47
	v_bfe_i32 v4, v3, 24, 1
	v_bfe_i32 v5, v3, 0, 1
	v_bfe_i32 v6, v2, 1, 1
	v_bfe_i32 v8, v2, 2, 1
	v_bfe_i32 v10, v2, 3, 1
	v_bfe_i32 v12, v2, 8, 1
	s_nop 0
	v_bfi_b32 v60, v4, v60, v47
	v_bfe_i32 v4, v2, 25, 1
	v_bfe_i32 v14, v2, 9, 1
	v_bfe_i32 v42, v2, 10, 1
	v_bfe_i32 v80, v2, 11, 1
	v_bfe_i32 v82, v2, 16, 1
	v_bfe_i32 v84, v2, 17, 1
	v_bfe_i32 v86, v2, 18, 1
	v_bfe_i32 v88, v2, 19, 1
	v_bfe_i32 v90, v2, 24, 1
	v_bfi_b32 v48, v5, v48, v47
	v_bfe_i32 v5, v3, 25, 1
	s_nop 0
	v_bfi_b32 v77, v4, v77, v47
	v_bfe_i32 v4, v2, 26, 1
	v_bfe_i32 v2, v2, 27, 1
	v_bfe_i32 v7, v3, 1, 1
	v_bfe_i32 v9, v3, 2, 1
	v_bfe_i32 v11, v3, 3, 1
	v_bfe_i32 v13, v3, 8, 1
	v_bfe_i32 v15, v3, 9, 1
	v_bfe_i32 v43, v3, 10, 1
	v_bfe_i32 v81, v3, 11, 1
	v_bfe_i32 v83, v3, 16, 1
	v_bfe_i32 v85, v3, 17, 1
	v_bfe_i32 v87, v3, 18, 1
	v_bfe_i32 v89, v3, 19, 1
	v_bfi_b32 v65, v6, v65, v47
	v_bfi_b32 v61, v5, v61, v47
	v_bfe_i32 v5, v3, 26, 1
	v_bfe_i32 v3, v3, 27, 1
	s_nop 0
	v_bfi_b32 v79, v2, v79, v47
	v_bfi_b32 v49, v7, v49, v47
	v_max3_f32 v2, v64, v65, v48
	v_bfi_b32 v66, v8, v66, v47
	v_bfi_b32 v50, v9, v50, v47
	v_bfi_b32 v67, v10, v67, v47
	v_bfi_b32 v51, v11, v51, v47
	v_bfi_b32 v63, v3, v63, v47
	v_bfi_b32 v68, v12, v68, v47
	v_bfi_b32 v69, v14, v69, v47
	v_bfi_b32 v70, v42, v70, v47
	s_nop 0
	v_max3_f32 v3, v66, v67, v49
	v_max3_f32 v2, v2, v50, v51
	v_bfi_b32 v71, v80, v71, v47
	v_bfi_b32 v52, v13, v52, v47
	v_bfi_b32 v53, v15, v53, v47
	v_bfi_b32 v54, v43, v54, v47
	v_bfi_b32 v55, v81, v55, v47
	s_nop 0
	v_max3_f32 v2, v2, v68, v69
	v_max3_f32 v3, v3, v70, v71
	v_bfi_b32 v72, v82, v72, v47
	v_bfi_b32 v73, v84, v73, v47
	v_bfi_b32 v74, v86, v74, v47
	v_bfi_b32 v75, v88, v75, v47
	s_nop 0
	v_max3_f32 v2, v2, v52, v53
	v_max3_f32 v3, v3, v54, v55
	v_bfi_b32 v56, v83, v56, v47
	v_bfi_b32 v57, v85, v57, v47
	v_bfi_b32 v58, v87, v58, v47
	v_bfi_b32 v59, v89, v59, v47
	s_nop 0
	v_max3_f32 v2, v2, v72, v73
	v_max3_f32 v3, v3, v74, v75
	v_bfi_b32 v76, v90, v76, v47
	v_bfi_b32 v78, v4, v78, v47
	v_bfi_b32 v62, v5, v62, v47
	s_nop 0
	v_max3_f32 v2, v2, v56, v57
	v_max3_f32 v3, v3, v58, v59
	s_nop 0
	v_max3_f32 v2, v2, v76, v77
	v_max3_f32 v3, v3, v78, v79
	s_nop 0
	v_max3_f32 v2, v2, v60, v61
	v_max3_f32 v3, v3, v62, v63
	s_nop 0
	v_max_f32_e32 v2, v2, v3
	s_nop 0
	v_mov_b32_e32 v3, v2
	s_nop 1
	v_permlane32_swap_b32_e32 v2, v3
	v_max_f32_e32 v2, v2, v3
	s_nop 0
	v_max_f32_e32 v2, v2, v2
	v_max_f32_e32 v2, 0xc1f00000, v2
	v_add_f32_e32 v225, v1, v2
	v_sub_f32_e32 v3, v64, v2
	v_sub_f32_e32 v4, v48, v2
	v_sub_f32_e32 v5, v65, v2
	v_sub_f32_e32 v6, v49, v2
	v_sub_f32_e32 v7, v66, v2
	s_nop 0
	v_xor_b32_e32 v80, 0x80000000, v225
	v_mov_b32_e32 v81, v80
	v_mov_b32_e32 v82, v80
	v_mov_b32_e32 v83, v80
	v_mov_b32_e32 v84, v80
	v_mov_b32_e32 v85, v80
	v_mov_b32_e32 v86, v80
	v_mov_b32_e32 v87, v80
	v_mov_b32_e32 v88, v80
	v_mov_b32_e32 v89, v80
	v_mov_b32_e32 v90, v80
	v_mov_b32_e32 v91, v80
	v_mov_b32_e32 v92, v80
	v_mov_b32_e32 v93, v80
	v_mov_b32_e32 v94, v80
	v_mov_b32_e32 v95, v80
	v_sub_f32_e32 v8, v50, v2
	v_sub_f32_e32 v9, v67, v2
	v_sub_f32_e32 v10, v51, v2
	v_sub_f32_e32 v11, v68, v2
	v_sub_f32_e32 v12, v52, v2
	v_sub_f32_e32 v13, v69, v2
	v_sub_f32_e32 v14, v53, v2
	v_sub_f32_e32 v15, v70, v2
	v_sub_f32_e32 v42, v54, v2
	v_sub_f32_e32 v43, v71, v2
	v_sub_f32_e32 v48, v55, v2
	v_sub_f32_e32 v49, v72, v2
	v_sub_f32_e32 v50, v56, v2
	v_sub_f32_e32 v51, v73, v2
	v_sub_f32_e32 v52, v57, v2
	v_sub_f32_e32 v53, v74, v2
	v_sub_f32_e32 v54, v58, v2
	v_sub_f32_e32 v55, v75, v2
	v_sub_f32_e32 v56, v59, v2
	v_sub_f32_e32 v57, v76, v2
	v_sub_f32_e32 v58, v60, v2
	v_sub_f32_e32 v59, v77, v2
	v_sub_f32_e32 v60, v61, v2
	v_sub_f32_e32 v61, v78, v2
	v_sub_f32_e32 v62, v62, v2
	v_sub_f32_e32 v64, v79, v2
	v_sub_f32_e32 v2, v63, v2
	s_waitcnt vmcnt(0) lgkmcnt(0)
	s_barrier
	v_exp_f32_e32 v112, v3
	v_exp_f32_e32 v111, v2
	v_lshl_add_u64 v[2:3], v[44:45], 0, s[52:53]
	s_mov_b32 s0, m0
	s_mov_b32 m0, s48
	s_nop 0
	global_load_lds_dwordx4 v[2:3], off
	s_mov_b32 m0, s0
	v_exp_f32_e32 v118, v15
	v_exp_f32_e32 v101, v14
	v_lshl_add_u64 v[14:15], v[40:41], 0, s[18:19]
	s_add_i32 s0, s49, 0x2000
	s_mov_b32 s1, m0
	s_mov_b32 m0, s0
	s_nop 0
	global_load_lds_dwordx4 v[14:15], off
	s_mov_b32 m0, s1
	ds_read_b128 v[198:201], v227 offset:8192
	ds_read_b128 v[194:197], v227 offset:8704
	ds_read_b128 v[190:193], v227 offset:10240
	ds_read_b128 v[186:189], v227 offset:10752
	ds_read_b128 v[182:185], v227 offset:12288
	ds_read_b128 v[178:181], v227 offset:12800
	ds_read_b128 v[174:177], v227 offset:14336
	ds_read_b128 v[170:173], v227 offset:14848
	v_exp_f32_e32 v113, v5
	v_exp_f32_e32 v114, v7
	v_exp_f32_e32 v115, v9
	v_exp_f32_e32 v116, v11
	v_exp_f32_e32 v117, v13
	v_exp_f32_e32 v119, v43
	v_exp_f32_e32 v120, v49
	v_exp_f32_e32 v121, v51
	v_exp_f32_e32 v122, v53
	v_exp_f32_e32 v123, v55
	v_exp_f32_e32 v124, v57
	v_exp_f32_e32 v125, v59
	v_exp_f32_e32 v126, v61
	v_exp_f32_e32 v127, v64
	v_exp_f32_e32 v96, v4
	v_exp_f32_e32 v97, v6
	v_exp_f32_e32 v98, v8
	v_exp_f32_e32 v99, v10
	v_exp_f32_e32 v100, v12
	v_exp_f32_e32 v102, v42
	v_exp_f32_e32 v103, v48
	v_exp_f32_e32 v104, v50
	v_exp_f32_e32 v105, v52
	v_exp_f32_e32 v106, v54
	v_exp_f32_e32 v107, v56
	v_exp_f32_e32 v108, v58
	v_exp_f32_e32 v109, v60
	v_exp_f32_e32 v110, v62
	s_waitcnt vmcnt(2) lgkmcnt(0)
	s_barrier
	s_cbranch_vccz .LBB0_1532
	s_mov_b64 s[0:1], 0xa000
	v_lshl_add_u64 v[208:209], v[44:45], 0, s[0:1]
	s_add_i32 s0, s46, 0xc900
	v_mov_b32_e32 v128, 0
	s_add_i32 s22, s50, -5
	v_lshl_add_u64 v[206:207], v[40:41], 0, s[52:53]
	v_add_u32_e32 v129, s0, v210
	s_movk_i32 s34, 0x4000
	s_movk_i32 s23, 0x2000
	s_mov_b32 s0, 0
	v_mov_b32_e32 v48, 0
	v_mov_b32_e32 v49, v128
	v_mov_b32_e32 v50, v128
	v_mov_b32_e32 v51, v128
	v_mov_b32_e32 v52, v128
	v_mov_b32_e32 v53, v128
	v_mov_b32_e32 v54, v128
	v_mov_b32_e32 v55, v128
	v_mov_b32_e32 v56, v128
	v_mov_b32_e32 v57, v128
	v_mov_b32_e32 v58, v128
	v_mov_b32_e32 v59, v128
	v_mov_b32_e32 v60, v128
	v_mov_b32_e32 v61, v128
	v_mov_b32_e32 v62, v128
	v_mov_b32_e32 v63, v128
	v_mov_b32_e32 v64, 0
	v_mov_b32_e32 v65, v128
	v_mov_b32_e32 v66, v128
	v_mov_b32_e32 v67, v128
	v_mov_b32_e32 v68, v128
	v_mov_b32_e32 v69, v128
	v_mov_b32_e32 v70, v128
	v_mov_b32_e32 v71, v128
	v_mov_b32_e32 v72, v128
	v_mov_b32_e32 v73, v128
	v_mov_b32_e32 v74, v128
	v_mov_b32_e32 v75, v128
	v_mov_b32_e32 v76, v128
	v_mov_b32_e32 v77, v128
	v_mov_b32_e32 v78, v128
	v_mov_b32_e32 v79, v128
